# combined strip map + thresholded rescale + row-max tree without the redundant canonicalising v_max in the attention tile body (same alignment of the tile body)
# baseline (speedup 1.0000x reference)
; template <int NKS, bool ALLIN = false> ...
;     ...
;             float mx = -INFINITY;
; #pragma unroll
;             for (int i = 0; i < 16; ++i) mx = fmaxf(mx, fmaxf(s0[i], s1[i]));
;             mx = fmaxf(mx, __shfl_xor(mx, 32)) * c2;
;             const float mnew = fmaxf(mrun, mx), alpha = __builtin_amdgcn_exp2f(mrun - mnew); mrun = mnew;
.LBB0_108:
	s_and_b32 s19, s22, 1
	s_mul_i32 s22, s19, 0x6400
	v_add_u32_e32 v0, s22, v215
	ds_read_b128 v[2:5], v0
	ds_read_b128 v[6:9], v0 offset:32
	ds_read_b128 v[10:13], v0 offset:12800
	ds_read_b128 v[180:183], v0 offset:12832
	ds_read_b128 v[184:187], v0 offset:64
	ds_read_b128 v[188:191], v0 offset:96
	ds_read_b128 v[192:195], v0 offset:12864
	ds_read_b128 v[196:199], v0 offset:12896
	s_mulk_i32 s19, 0x5000
	s_waitcnt lgkmcnt(7)
	v_mfma_f32_32x32x16_bf16 v[96:111], v[2:5], v[132:135], 0
	s_waitcnt lgkmcnt(5)
	v_mfma_f32_32x32x16_bf16 v[80:95], v[10:13], v[132:135], 0
	v_mfma_f32_32x32x16_bf16 v[96:111], v[6:9], v[136:139], v[96:111]
	s_waitcnt lgkmcnt(4)
	v_mfma_f32_32x32x16_bf16 v[80:95], v[180:183], v[136:139], v[80:95]
	ds_read_b128 v[2:5], v0 offset:128
	ds_read_b128 v[6:9], v0 offset:160
	ds_read_b128 v[10:13], v0 offset:12928
	ds_read_b128 v[180:183], v0 offset:12960
	s_waitcnt lgkmcnt(7)
	v_mfma_f32_32x32x16_bf16 v[96:111], v[184:187], v[140:143], v[96:111]
	s_waitcnt lgkmcnt(5)
	v_mfma_f32_32x32x16_bf16 v[80:95], v[192:195], v[140:143], v[80:95]
	v_mfma_f32_32x32x16_bf16 v[96:111], v[188:191], v[144:147], v[96:111]
	s_waitcnt lgkmcnt(4)
	v_mfma_f32_32x32x16_bf16 v[80:95], v[196:199], v[144:147], v[80:95]
	ds_read_b128 v[184:187], v0 offset:192
	ds_read_b128 v[188:191], v0 offset:224
	ds_read_b128 v[192:195], v0 offset:12992
	ds_read_b128 v[196:199], v0 offset:13024
	s_waitcnt lgkmcnt(7)
	v_mfma_f32_32x32x16_bf16 v[96:111], v[2:5], v[148:151], v[96:111]
	s_waitcnt lgkmcnt(5)
	v_mfma_f32_32x32x16_bf16 v[80:95], v[10:13], v[148:151], v[80:95]
	v_mfma_f32_32x32x16_bf16 v[96:111], v[6:9], v[152:155], v[96:111]
	s_waitcnt lgkmcnt(4)
	v_mfma_f32_32x32x16_bf16 v[80:95], v[180:183], v[152:155], v[80:95]
	ds_read_b128 v[2:5], v0 offset:256
	ds_read_b128 v[6:9], v0 offset:288
	ds_read_b128 v[10:13], v0 offset:13056
	ds_read_b128 v[180:183], v0 offset:13088
	s_waitcnt lgkmcnt(7)
	v_mfma_f32_32x32x16_bf16 v[96:111], v[184:187], v[156:159], v[96:111]
	s_waitcnt lgkmcnt(5)
	v_mfma_f32_32x32x16_bf16 v[80:95], v[192:195], v[156:159], v[80:95]
	v_mfma_f32_32x32x16_bf16 v[96:111], v[188:191], v[160:163], v[96:111]
	s_waitcnt lgkmcnt(4)
	v_mfma_f32_32x32x16_bf16 v[80:95], v[196:199], v[160:163], v[80:95]
	ds_read_b128 v[184:187], v0 offset:320
	ds_read_b128 v[188:191], v0 offset:352
	ds_read_b128 v[192:195], v0 offset:13120
	ds_read_b128 v[196:199], v0 offset:13152
	s_waitcnt lgkmcnt(7)
	v_mfma_f32_32x32x16_bf16 v[96:111], v[2:5], v[164:167], v[96:111]
	s_waitcnt lgkmcnt(5)
	v_mfma_f32_32x32x16_bf16 v[80:95], v[10:13], v[164:167], v[80:95]
	v_mfma_f32_32x32x16_bf16 v[96:111], v[6:9], v[168:171], v[96:111]
	s_waitcnt lgkmcnt(4)
	v_mfma_f32_32x32x16_bf16 v[80:95], v[180:183], v[168:171], v[80:95]
	s_waitcnt lgkmcnt(3)
	v_mfma_f32_32x32x16_bf16 v[96:111], v[184:187], v[172:175], v[96:111]
	s_waitcnt lgkmcnt(1)
	v_mfma_f32_32x32x16_bf16 v[80:95], v[192:195], v[172:175], v[80:95]
	v_mfma_f32_32x32x16_bf16 v[96:111], v[188:191], v[176:179], v[96:111]
	s_waitcnt lgkmcnt(0)
	v_mfma_f32_32x32x16_bf16 v[80:95], v[196:199], v[176:179], v[80:95]
	v_add_u32_e32 v222, s19, v213
	v_add_u32_e32 v218, 0xc800, v222
	ds_read_b64_tr_b16 v[184:185], v222 offset:51200
	ds_read_b64_tr_b16 v[186:187], v222 offset:53760
	ds_read_b64_tr_b16 v[182:183], v222 offset:53824
	ds_read_b64_tr_b16 v[180:181], v222 offset:51264
	ds_read_b64_tr_b16 v[196:197], v222 offset:56320
	ds_read_b64_tr_b16 v[198:199], v222 offset:58880
	ds_read_b64_tr_b16 v[12:13], v222 offset:58944
	ds_read_b64_tr_b16 v[10:11], v222 offset:56384
	ds_read_b64_tr_b16 v[192:193], v222 offset:61440
	ds_read_b64_tr_b16 v[194:195], v222 offset:64000
	ds_read_b64_tr_b16 v[8:9], v222 offset:64064
	ds_read_b64_tr_b16 v[6:7], v222 offset:61504
	ds_read_b64_tr_b16 v[188:189], v218 offset:15360
	ds_read_b64_tr_b16 v[190:191], v218 offset:17920
	ds_read_b64_tr_b16 v[4:5], v218 offset:17984
	ds_read_b64_tr_b16 v[2:3], v218 offset:15424
	v_max3_f32 v0, v80, v96, s73
	v_max3_f32 v14, v81, v97, s73
	v_max3_f32 v0, v0, v82, v98
	v_max3_f32 v14, v14, v83, v99
	v_max3_f32 v0, v0, v84, v100
	v_max3_f32 v14, v14, v85, v101
	v_max3_f32 v0, v0, v86, v102
	v_max3_f32 v14, v14, v87, v103
	v_max3_f32 v0, v0, v88, v104
	v_max3_f32 v14, v14, v89, v105
	v_max3_f32 v0, v0, v90, v106
	v_max3_f32 v14, v14, v91, v107
	v_max3_f32 v0, v0, v92, v108
	v_max3_f32 v14, v14, v93, v109
	v_max3_f32 v0, v0, v94, v110
	v_max3_f32 v14, v14, v95, v111
	v_max_f32_e32 v0, v0, v14
	v_and_b32_e32 v15, 64, v220
	v_xor_b32_e32 v14, 32, v220
	v_add_u32_e32 v15, 64, v15
	v_cmp_lt_i32_e32 vcc, v14, v15
	s_nop 1
	v_cndmask_b32_e32 v14, v220, v14, vcc
	v_lshlrev_b32_e32 v14, 2, v14
	ds_bpermute_b32 v14, v14, v0
	s_waitcnt lgkmcnt(0)
	v_max_f32_e32 v14, v14, v14
	v_max_f32_e32 v0, v0, v14
	v_mul_f32_e32 v0, 0x3dd53b94, v0
	v_max_f32_e32 v14, v219, v219
	v_max_f32_e32 v223, v14, v0
	v_sub_f32_e32 v15, v223, v14
	v_cmp_lt_f32_e32 vcc, 0x41000000, v15
	s_cbranch_vccnz .Latt_upd
	v_mov_b32_e32 v223, v14

; #define MFMA32(a, b, c) __builtin_amdgcn_mfma_f32_32x32x16_bf16((a), (b), (c), 0, 0, 0)
; __device__ __forceinline__ bf16x8 cat44(s16x4 lo, s16x4 hi) { return (bf16x8){lo[0], lo[1], lo[2], lo[3], hi[0], hi[1], hi[2], hi[3]}; }
; #define ATT_LDV(buf, d) do { _Pragma("unroll") for (int kb = 0; kb < 2; ++kb) _Pragma("unroll") for (int s = 0; s < 2; ++s) { \
;                 const LAS unsigned char* p_ = Vb + vlane + (32 * kb + 16 * s) * VSTR + (d) * 64; vl[buf][2 * kb + s] = trread(p_); vh[buf][2 * kb + s] = trread(p_ + 8 * VSTR); } } while (0)
; template <int NKS, bool ALLIN = false> ...
;     ...
;             lrun = lrun * alpha + ls;
;     ...
;             __builtin_amdgcn_sched_barrier(0);
; #pragma unroll
;             for (int d = 0; d < 4; ++d) {
; #pragma unroll
;                 for (int j = 0; j < 4; ++j) o[d] = MFMA32(cat44(vl[d & 1][j], vh[d & 1][j]), pf[j], o[d]);
;                 __builtin_amdgcn_sched_barrier(0);
;                 if (d + 2 < 4) { ATT_LDV(d & 1, d + 2); __builtin_amdgcn_sched_barrier(0); }
;             }
.Latt_st_skip:
	s_nop 0
	v_mfma_f32_32x32x16_bf16 v[64:79], v[184:187], v[88:91], v[64:79]
	v_mfma_f32_32x32x16_bf16 v[64:79], v[196:199], v[92:95], v[64:79]
	v_mfma_f32_32x32x16_bf16 v[64:79], v[192:195], v[96:99], v[64:79]
	v_mfma_f32_32x32x16_bf16 v[64:79], v[188:191], v[80:83], v[64:79]
	ds_read_b64_tr_b16 v[84:85], v222 offset:51328
	ds_read_b64_tr_b16 v[86:87], v222 offset:53888
	ds_read_b64_tr_b16 v[100:101], v222 offset:56448
	ds_read_b64_tr_b16 v[102:103], v222 offset:59008
	ds_read_b64_tr_b16 v[104:105], v222 offset:61568
	ds_read_b64_tr_b16 v[106:107], v222 offset:64128
	ds_read_b64_tr_b16 v[108:109], v218 offset:15488
	ds_read_b64_tr_b16 v[110:111], v218 offset:18048
	v_mfma_f32_32x32x16_bf16 v[48:63], v[180:183], v[88:91], v[48:63]
	v_mfma_f32_32x32x16_bf16 v[48:63], v[10:13], v[92:95], v[48:63]
	v_mfma_f32_32x32x16_bf16 v[48:63], v[6:9], v[96:99], v[48:63]
	v_mfma_f32_32x32x16_bf16 v[48:63], v[2:5], v[80:83], v[48:63]
	ds_read_b64_tr_b16 v[2:3], v222 offset:51392
	ds_read_b64_tr_b16 v[4:5], v222 offset:53952
	ds_read_b64_tr_b16 v[6:7], v222 offset:56512
	ds_read_b64_tr_b16 v[8:9], v222 offset:59072
	ds_read_b64_tr_b16 v[10:11], v222 offset:61632
	ds_read_b64_tr_b16 v[12:13], v222 offset:64192
	ds_read_b64_tr_b16 v[180:181], v218 offset:15552
	ds_read_b64_tr_b16 v[182:183], v218 offset:18112
	s_waitcnt lgkmcnt(14)
	v_mfma_f32_32x32x16_bf16 v[32:47], v[84:87], v[88:91], v[32:47]
	s_waitcnt lgkmcnt(12)
	v_mfma_f32_32x32x16_bf16 v[32:47], v[100:103], v[92:95], v[32:47]
	s_waitcnt lgkmcnt(10)
	v_mfma_f32_32x32x16_bf16 v[32:47], v[104:107], v[96:99], v[32:47]
	s_waitcnt lgkmcnt(8)
	v_mfma_f32_32x32x16_bf16 v[32:47], v[108:111], v[80:83], v[32:47]
	s_waitcnt lgkmcnt(6)
	v_mfma_f32_32x32x16_bf16 v[16:31], v[2:5], v[88:91], v[16:31]
	s_waitcnt lgkmcnt(4)
	v_mfma_f32_32x32x16_bf16 v[16:31], v[6:9], v[92:95], v[16:31]
	s_waitcnt lgkmcnt(2)
	v_mfma_f32_32x32x16_bf16 v[16:31], v[10:13], v[96:99], v[16:31]
	s_waitcnt lgkmcnt(0)
	v_mfma_f32_32x32x16_bf16 v[16:31], v[180:183], v[80:83], v[16:31]
	v_fmac_f32_e32 v219, v214, v0
	v_mov_b32_e32 v214, v219
	v_mov_b32_e32 v219, v223
	s_branch .LBB0_105
	s_nop 0
	s_nop 0
	s_nop 0
	s_nop 0
	s_nop 0
	s_nop 0
	s_nop 0
	s_nop 0
	s_nop 0
	s_nop 0
	s_nop 0
	s_nop 0
	s_nop 0
	s_nop 0
	s_nop 0
	s_nop 0
	s_nop 0
	s_nop 0
	s_nop 0
	s_nop 0
	s_nop 0
	s_nop 0
	s_nop 0
	s_nop 0
	s_nop 0
	s_nop 0
	s_nop 0
	s_nop 0
	s_nop 0
	s_nop 0
	s_nop 0
